# MoBA tile loop unrolled x2 with two K/V staging register sets: global prefetch distance 2 tiles instead of 1
# speedup vs baseline: 1.0265x; 1.0090x over previous
; #define ALAS __attribute__((address_space(3)))
; __device__ __forceinline__ void moba_unit(int b, int h, int j, const bf16_t* Q, const bf16_t* K, const bf16_t* VT, bf16_t* O, const float* biasd, const float* kmean, ALAS unsigned char* lds) {
;     ...
;     { const int n = tid >> 5, d2 = (tid & 31) * 2; const float* kmp = kmean + (size_t)(b * 16 + n) * 2048 + h * 64 + d2; const float v0 = kmp[0] + kmp[1024], v1 = kmp[1] + kmp[1025];
;       const unsigned wh = cvtpk(v0, v1); const float h0 = __uint_as_float(wh << 16), h1 = __uint_as_float(wh & 0xffff0000u); const unsigned wl = cvtpk(v0 - h0, v1 - h1);
;       *(ALAS unsigned*)(lds + 37888 + n * ROWB + d2 * 2) = wh; *(ALAS unsigned*)(lds + 40192 + n * ROWB + d2 * 2) = wl; }
;     bf16x8 qf[4];
;     { const bf16_t* qp = Q + (tok0 + qpos) * 1024 + h * 64 + hi * 8;
; #pragma unroll
;       for (int d0 = 0; d0 < 4; ++d0) qf[d0] = *(const bf16x8*)(qp + d0 * 16); }
;     const int NT = 4 * (j + 1);
;     const int key = tid >> 3, part = tid & 7;
;     const bf16_t* kg = K + (tok0 + key) * 1024 + h * 64 + part * 8; const int kl = key * ROWB + part * 16;
;     const bf16_t* vg = VT + (size_t)(h * 64 + key) * MTOK + tok0 + part * 8; const int vl = 9216 + key * ROWB + part * 16;
;     u32x4 kr, vr;
;     { const int kb0 = 256 * j; kr = *(const u32x4*)(kg + (size_t)kb0 * 1024); vr = *(const u32x4*)(vg + kb0); }
;     __syncthreads();
;     unsigned selmask = 0u;
;     {
;         f32x16 g;
; #pragma unroll
;         for (int r = 0; r < 16; ++r) g[r] = 0.f;
;         const ALAS unsigned char* kp = lds + 37888 + (r32 & 15) * ROWB + hi * 16;
; #pragma unroll
;         for (int d0 = 0; d0 < 4; ++d0) {
;             const bf16x8 ah = *(const ALAS bf16x8*)(kp + d0 * 32), al = *(const ALAS bf16x8*)(kp + 2304 + d0 * 32);
;             g = __builtin_amdgcn_mfma_f32_32x32x16_bf16(ah, qf[d0], g, 0, 0, 0);
;             g = __builtin_amdgcn_mfma_f32_32x32x16_bf16(al, qf[d0], g, 0, 0, 0);
;         }
;         float gv[16];
; #pragma unroll
;         for (int r = 0; r < 8; ++r) { const float own = g[r], oth = __shfl_xor(own, 32); const int n0 = (r & 3) + 8 * (r >> 2);
;             gv[n0] = hi ? oth : own; gv[n0 + 4] = hi ? own : oth; }
; #pragma unroll
;         for (int n = 0; n < 16; ++n) gv[n] = (n < j) ? gv[n] : -INFINITY;
; #pragma unroll
;         for (int n = 0; n < 16; ++n) { int rank = 0;
; #pragma unroll
.Lmoba_bias_done:
	s_cmp_lt_i32 s37, 0
	v_pk_add_f32 v[12:13], v[12:13], v[14:15]
	s_nop 0
	v_cvt_pk_bf16_f32 v16, v12, v13
	v_lshlrev_b32_e32 v14, 16, v16
	v_and_b32_e32 v15, 0xffff0000, v16
	v_pk_add_f32 v[12:13], v[12:13], v[14:15] neg_lo:[0,1] neg_hi:[0,1]
	s_nop 0
	v_cvt_pk_bf16_f32 v12, v12, v13
	ds_write2st64_b32 v9, v16, v12 offset0:148 offset1:157
	s_waitcnt lgkmcnt(0)
	s_barrier
	ds_read_b128 v[12:15], v20 offset:37888
	s_waitcnt vmcnt(6) lgkmcnt(0)
	v_mfma_f32_32x32x16_bf16 v[32:47], v[12:15], v[64:67], 0
	ds_read_b128 v[12:15], v20 offset:40192
	v_xor_b32_e32 v9, 32, v203
	s_waitcnt lgkmcnt(0)
	v_mfma_f32_32x32x16_bf16 v[32:47], v[12:15], v[64:67], v[32:47]
	ds_read_b128 v[12:15], v20 offset:37920
	s_waitcnt vmcnt(5) lgkmcnt(0)
	v_mfma_f32_32x32x16_bf16 v[32:47], v[12:15], v[68:71], v[32:47]
	ds_read_b128 v[12:15], v20 offset:40224
	s_waitcnt lgkmcnt(0)
	v_mfma_f32_32x32x16_bf16 v[32:47], v[12:15], v[68:71], v[32:47]
	ds_read_b128 v[12:15], v20 offset:37952
	ds_read_b128 v[16:19], v20 offset:40256
	s_waitcnt vmcnt(4) lgkmcnt(1)
	v_mfma_f32_32x32x16_bf16 v[32:47], v[12:15], v[72:75], v[32:47]
	ds_read_b128 v[12:15], v20 offset:37984
	s_waitcnt lgkmcnt(1)
	v_mfma_f32_32x32x16_bf16 v[32:47], v[16:19], v[72:75], v[32:47]
	ds_read_b128 v[16:19], v20 offset:40288
	s_waitcnt vmcnt(1) lgkmcnt(1)
	v_mfma_f32_32x32x16_bf16 v[32:47], v[12:15], v[76:79], v[32:47]
	v_and_b32_e32 v12, 64, v203
	v_add_u32_e32 v12, 64, v12
	v_cmp_lt_i32_e32 vcc, v9, v12
	s_nop 1
	v_cndmask_b32_e32 v9, v203, v9, vcc
	v_lshlrev_b32_e32 v93, 2, v9
	s_waitcnt lgkmcnt(0)
	v_mfma_f32_32x32x16_bf16 v[32:47], v[16:19], v[76:79], v[32:47]
	s_nop 11
	ds_bpermute_b32 v42, v93, v32
	ds_bpermute_b32 v50, v93, v33
	ds_bpermute_b32 v49, v93, v34
	ds_bpermute_b32 v47, v93, v35
	ds_bpermute_b32 v46, v93, v36
	ds_bpermute_b32 v45, v93, v37
	ds_bpermute_b32 v43, v93, v38
	ds_bpermute_b32 v44, v93, v39
	s_cbranch_scc1 .LBB0_516
	v_mul_lo_u32 v104, v8, s39
	s_or_b32 s4, s96, 64
	v_add3_u32 v8, 0, v104, v92
	s_lshl_b64 s[6:7], s[4:5], 11
	ds_write_b128 v8, v[0:3]
	s_waitcnt vmcnt(0)
	ds_write_b128 v8, v[4:7] offset:9216
	v_lshl_add_u64 v[0:1], v[94:95], 0, s[6:7]
	s_mov_b32 s97, s5
	s_waitcnt lgkmcnt(0)
	s_barrier
	v_lshl_add_u64 v[2:3], s[96:97], 1, v[96:97]
	global_load_dwordx4 v[80:83], v[0:1], off
	global_load_dwordx4 v[84:87], v[2:3], off offset:128
	s_add_i32 s6, s96, 0x80
	s_mov_b32 s7, s5
	s_lshl_b64 s[6:7], s[6:7], 11
	v_lshl_add_u64 v[0:1], v[94:95], 0, s[6:7]
	global_load_dwordx4 v[160:163], v[0:1], off
	global_load_dwordx4 v[164:167], v[2:3], off offset:256
	v_lshlrev_b32_e32 v1, 1, v11
	v_lshrrev_b32_e32 v2, 1, v10
	v_and_b32_e32 v0, 19, v10
	v_and_b32_e32 v1, 8, v1
	v_and_b32_e32 v2, 4, v2
	s_sub_i32 s4, s1, 63
	v_or3_b32 v0, v2, v0, v1
	v_mul_u32_u24_e32 v105, 0x90, v0
	s_cmp_lt_i32 s38, 0
	v_mul_u32_u24_e32 v106, 0x90, v11
	s_cbranch_scc1 .LBB0_530
	v_add3_u32 v1, 0, v105, v144
	ds_read_b128 v[52:55], v1 offset:0
	ds_read_b128 v[56:59], v1 offset:4608
	ds_read_b128 v[60:63], v1 offset:32
	ds_read_b128 v[100:103], v1 offset:4640
	ds_read_b128 v[108:111], v1 offset:64
	ds_read_b128 v[112:115], v1 offset:4672
	s_sub_i32 s1, s4, s96
	ds_read_b128 v[116:119], v1 offset:96
	s_cmpk_gt_i32 s1, 0x7f
	ds_read_b128 v[120:123], v1 offset:4704
	s_cselect_b64 vcc, -1, 0
	v_cndmask_b32_e32 v0, 0, v99, vcc
	v_mov_b32_e32 v1, v0
	v_mov_b32_e32 v2, v0
	v_mov_b32_e32 v3, v0
	v_mov_b32_e32 v4, v0
	v_mov_b32_e32 v5, v0
	v_mov_b32_e32 v6, v0
	v_mov_b32_e32 v7, v0
	v_mov_b32_e32 v8, v0
	v_mov_b32_e32 v9, v0
	v_mov_b32_e32 v10, v0
	v_mov_b32_e32 v11, v0
	v_mov_b32_e32 v12, v0
	v_mov_b32_e32 v13, v0
	v_mov_b32_e32 v14, v0
	v_mov_b32_e32 v15, v0
	s_waitcnt lgkmcnt(6)
	s_nop 1
	v_mfma_f32_32x32x16_bf16 v[16:31], v[52:55], v[64:67], v[0:15]
	s_and_b64 vcc, exec, vcc
	v_mfma_f32_32x32x16_bf16 v[0:15], v[56:59], v[64:67], v[0:15]
	s_waitcnt lgkmcnt(4)
	v_mfma_f32_32x32x16_bf16 v[16:31], v[60:63], v[68:71], v[16:31]
	v_mfma_f32_32x32x16_bf16 v[0:15], v[100:103], v[68:71], v[0:15]
	s_waitcnt lgkmcnt(2)
	v_mfma_f32_32x32x16_bf16 v[16:31], v[108:111], v[72:75], v[16:31]
	v_mfma_f32_32x32x16_bf16 v[0:15], v[112:115], v[72:75], v[0:15]
	s_waitcnt lgkmcnt(0)
	v_mfma_f32_32x32x16_bf16 v[16:31], v[116:119], v[76:79], v[16:31]
	v_mfma_f32_32x32x16_bf16 v[0:15], v[120:123], v[76:79], v[0:15]
	s_cbranch_vccnz .LBB0_528
; #define ALAS __attribute__((address_space(3)))
; __device__ __forceinline__ void near_bias(f32x16& s0, f32x16& s1, const ALAS float* bt, int qpos, int kbase, int hi) {
; #pragma unroll
;     for (int r = 0; r < 16; ++r) {
;         const int d0 = qpos - (kbase + (r & 7) + 8 * hi + 16 * (r >> 3)), d1 = d0 - 32;
;         const float b0 = bt[min(max(d0, 0), 255)], b1 = bt[min(max(d1, 0), 255)];
;         s0[r] = d0 < 0 ? NEG : s0[r] + b0; s1[r] = d1 < 0 ? NEG : s1[r] + b1;
;     }
; }
	v_or_b32_e32 v51, s96, v98
	v_xad_u32 v107, v51, -1, v90
	v_med3_i32 v52, v107, 0, v204
	v_lshl_add_u32 v53, v52, 2, 0
	v_max_i32_e32 v52, 32, v107
	v_subrev_u32_e32 v52, 32, v52
	v_min_u32_e32 v52, 0xff, v52
	v_or_b32_e32 v55, 2, v51
	v_lshl_add_u32 v54, v52, 2, 0
	v_or_b32_e32 v52, 3, v51
	v_sub_u32_e32 v123, v90, v55
	v_sub_u32_e32 v122, v90, v52
	v_med3_i32 v52, v123, 0, v204
	v_lshl_add_u32 v55, v52, 2, 0
	v_max_i32_e32 v52, 32, v123
	v_subrev_u32_e32 v52, 32, v52
	v_min_u32_e32 v52, 0xff, v52
	v_sub_u32_e32 v91, v90, v51
	v_lshl_add_u32 v56, v52, 2, 0
	v_max_i32_e32 v52, 32, v122
	v_max_i32_e32 v41, 32, v91
	v_subrev_u32_e32 v52, 32, v52
	v_subrev_u32_e32 v41, 32, v41
	v_min_u32_e32 v52, 0xff, v52
	v_med3_i32 v40, v91, 0, v204
	v_min_u32_e32 v41, 0xff, v41
	v_lshl_add_u32 v57, v52, 2, 0
	v_med3_i32 v52, v122, 0, v204
	v_lshl_add_u32 v40, v40, 2, 0
	v_lshl_add_u32 v41, v41, 2, 0
	v_lshl_add_u32 v58, v52, 2, 0
	ds_read_b32 v52, v40 offset:36864
	ds_read_b32 v40, v41 offset:36864
	ds_read_b32 v53, v53 offset:36864
	ds_read_b32 v41, v54 offset:36864
	ds_read_b32 v54, v55 offset:36864
	ds_read_b32 v56, v56 offset:36864
	ds_read_b32 v57, v57 offset:36864
	ds_read_b32 v55, v58 offset:36864
	v_or_b32_e32 v58, 5, v51
	v_sub_u32_e32 v124, v90, v58
	v_max_i32_e32 v60, 32, v124
	v_subrev_u32_e32 v60, 32, v60
	v_min_u32_e32 v60, 0xff, v60
	v_lshl_add_u32 v61, v60, 2, 0
	v_med3_i32 v60, v124, 0, v204
	v_or_b32_e32 v63, 6, v51
	v_lshl_add_u32 v62, v60, 2, 0
	v_or_b32_e32 v60, 7, v51
	v_sub_u32_e32 v127, v90, v63
	v_sub_u32_e32 v126, v90, v60
	v_med3_i32 v60, v127, 0, v204
	v_lshl_add_u32 v63, v60, 2, 0
	v_max_i32_e32 v60, 32, v127
	v_subrev_u32_e32 v60, 32, v60
	v_or_b32_e32 v59, 4, v51
	v_min_u32_e32 v60, 0xff, v60
	v_sub_u32_e32 v125, v90, v59
	v_lshl_add_u32 v100, v60, 2, 0
	v_max_i32_e32 v60, 32, v126
	v_max_i32_e32 v59, 32, v125
	v_subrev_u32_e32 v60, 32, v60
	v_subrev_u32_e32 v59, 32, v59
	v_min_u32_e32 v60, 0xff, v60
	v_med3_i32 v58, v125, 0, v204
	v_min_u32_e32 v59, 0xff, v59
	v_lshl_add_u32 v101, v60, 2, 0
	v_med3_i32 v60, v126, 0, v204
	v_lshl_add_u32 v58, v58, 2, 0
	v_lshl_add_u32 v59, v59, 2, 0
	v_lshl_add_u32 v102, v60, 2, 0
	ds_read_b32 v58, v58 offset:36864
	ds_read_b32 v60, v59 offset:36864
	ds_read_b32 v61, v61 offset:36864
	ds_read_b32 v59, v62 offset:36864
	ds_read_b32 v62, v63 offset:36864
	ds_read_b32 v100, v100 offset:36864
	ds_read_b32 v101, v101 offset:36864
	ds_read_b32 v63, v102 offset:36864
	v_or_b32_e32 v102, 17, v51
	v_sub_u32_e32 v128, v90, v102
	v_max_i32_e32 v108, 32, v128
	v_subrev_u32_e32 v108, 32, v108
	v_min_u32_e32 v108, 0xff, v108
	v_lshl_add_u32 v109, v108, 2, 0
	v_med3_i32 v108, v128, 0, v204
	v_or_b32_e32 v111, 18, v51
	v_lshl_add_u32 v110, v108, 2, 0
	v_or_b32_e32 v108, 19, v51
	v_sub_u32_e32 v131, v90, v111
	v_sub_u32_e32 v130, v90, v108
	v_med3_i32 v108, v131, 0, v204
	v_lshl_add_u32 v111, v108, 2, 0
	v_max_i32_e32 v108, 32, v131
	v_subrev_u32_e32 v108, 32, v108
	v_or_b32_e32 v103, 16, v51
	v_min_u32_e32 v108, 0xff, v108
	v_sub_u32_e32 v129, v90, v103
	v_lshl_add_u32 v112, v108, 2, 0
	v_max_i32_e32 v108, 32, v130
	v_max_i32_e32 v103, 32, v129
	v_subrev_u32_e32 v108, 32, v108
	v_subrev_u32_e32 v103, 32, v103
	v_min_u32_e32 v108, 0xff, v108
	v_med3_i32 v102, v129, 0, v204
	v_min_u32_e32 v103, 0xff, v103
	v_lshl_add_u32 v113, v108, 2, 0
	v_med3_i32 v108, v130, 0, v204
	v_lshl_add_u32 v102, v102, 2, 0
	v_lshl_add_u32 v103, v103, 2, 0
	v_lshl_add_u32 v114, v108, 2, 0
	ds_read_b32 v102, v102 offset:36864
	ds_read_b32 v108, v103 offset:36864
	ds_read_b32 v109, v109 offset:36864
	ds_read_b32 v103, v110 offset:36864
	ds_read_b32 v110, v111 offset:36864
	ds_read_b32 v112, v112 offset:36864
	ds_read_b32 v113, v113 offset:36864
	ds_read_b32 v111, v114 offset:36864
	v_or_b32_e32 v114, 21, v51
	v_sub_u32_e32 v132, v90, v114
	v_max_i32_e32 v116, 32, v132
	v_subrev_u32_e32 v116, 32, v116
	v_min_u32_e32 v116, 0xff, v116
	v_lshl_add_u32 v117, v116, 2, 0
	v_med3_i32 v116, v132, 0, v204
	v_or_b32_e32 v115, 20, v51
	v_lshl_add_u32 v118, v116, 2, 0
	v_or_b32_e32 v116, 23, v51
	v_or_b32_e32 v51, 22, v51
	v_sub_u32_e32 v51, v90, v51
	v_sub_u32_e32 v134, v90, v116
	v_med3_i32 v116, v51, 0, v204
	v_lshl_add_u32 v119, v116, 2, 0
	v_max_i32_e32 v116, 32, v51
	v_subrev_u32_e32 v116, 32, v116
	v_sub_u32_e32 v133, v90, v115
	v_min_u32_e32 v116, 0xff, v116
	v_max_i32_e32 v115, 32, v133
	v_lshl_add_u32 v120, v116, 2, 0
	v_max_i32_e32 v116, 32, v134
	v_subrev_u32_e32 v115, 32, v115
	v_subrev_u32_e32 v116, 32, v116
	v_med3_i32 v114, v133, 0, v204
	v_min_u32_e32 v115, 0xff, v115
	v_min_u32_e32 v116, 0xff, v116
	v_lshl_add_u32 v114, v114, 2, 0
	v_lshl_add_u32 v115, v115, 2, 0
	v_lshl_add_u32 v121, v116, 2, 0
	v_med3_i32 v116, v134, 0, v204
	v_lshl_add_u32 v135, v116, 2, 0
	ds_read_b32 v114, v114 offset:36864
	ds_read_b32 v116, v115 offset:36864
	ds_read_b32 v117, v117 offset:36864
	ds_read_b32 v115, v118 offset:36864
	ds_read_b32 v118, v119 offset:36864
	ds_read_b32 v120, v120 offset:36864
	ds_read_b32 v121, v121 offset:36864
	ds_read_b32 v119, v135 offset:36864
	v_cmp_lt_i32_e32 vcc, -1, v134
	s_waitcnt lgkmcnt(4)
; __device__ __forceinline__ void near_bias(f32x16& s0, f32x16& s1, const ALAS float* bt, int qpos, int kbase, int hi) {
;     ...
;     for (int r = 0; r < 16; ++r) {
;         const int d0 = qpos - (kbase + (r & 7) + 8 * hi + 16 * (r >> 3)), d1 = d0 - 32;
;         const float b0 = bt[min(max(d0, 0), 255)], b1 = bt[min(max(d1, 0), 255)];
;         s0[r] = d0 < 0 ? NEG : s0[r] + b0; s1[r] = d1 < 0 ? NEG : s1[r] + b1;
;     }
	v_pk_add_f32 v[28:29], v[28:29], v[114:115]
	v_pk_add_f32 v[26:27], v[26:27], v[110:111]
	v_pk_add_f32 v[24:25], v[24:25], v[102:103]
	s_waitcnt lgkmcnt(0)
	v_pk_add_f32 v[30:31], v[30:31], v[118:119]
	v_pk_add_f32 v[22:23], v[22:23], v[62:63]
	v_cndmask_b32_e32 v31, v205, v31, vcc
	v_cmp_lt_i32_e32 vcc, -1, v51
	v_pk_add_f32 v[20:21], v[20:21], v[58:59]
	v_pk_add_f32 v[18:19], v[18:19], v[54:55]
	v_cndmask_b32_e32 v30, v205, v30, vcc
	v_cmp_lt_i32_e32 vcc, -1, v132
	v_pk_add_f32 v[16:17], v[16:17], v[52:53]
	v_pk_add_f32 v[14:15], v[14:15], v[120:121]
	v_cndmask_b32_e32 v29, v205, v29, vcc
	v_cmp_lt_i32_e32 vcc, -1, v133
	v_pk_add_f32 v[12:13], v[12:13], v[116:117]
	v_pk_add_f32 v[10:11], v[10:11], v[112:113]
	v_cndmask_b32_e32 v28, v205, v28, vcc
	v_cmp_lt_i32_e32 vcc, -1, v130
	v_pk_add_f32 v[8:9], v[8:9], v[108:109]
	v_pk_add_f32 v[6:7], v[6:7], v[100:101]
	v_cndmask_b32_e32 v27, v205, v27, vcc
	v_cmp_lt_i32_e32 vcc, -1, v131
	v_pk_add_f32 v[4:5], v[4:5], v[60:61]
	v_pk_add_f32 v[2:3], v[2:3], v[56:57]
	v_cndmask_b32_e32 v26, v205, v26, vcc
	v_cmp_lt_i32_e32 vcc, -1, v128
	v_pk_add_f32 v[0:1], v[0:1], v[40:41]
	s_nop 0
	v_cndmask_b32_e32 v25, v205, v25, vcc
	v_cmp_lt_i32_e32 vcc, -1, v129
	s_nop 1
	v_cndmask_b32_e32 v24, v205, v24, vcc
	v_cmp_lt_i32_e32 vcc, -1, v126
	s_nop 1
	v_cndmask_b32_e32 v23, v205, v23, vcc
	v_cmp_lt_i32_e32 vcc, -1, v127
	s_nop 1
	v_cndmask_b32_e32 v22, v205, v22, vcc
	v_cmp_lt_i32_e32 vcc, -1, v124
	s_nop 1
	v_cndmask_b32_e32 v21, v205, v21, vcc
	v_cmp_lt_i32_e32 vcc, -1, v125
	s_nop 1
	v_cndmask_b32_e32 v20, v205, v20, vcc
	v_cmp_lt_i32_e32 vcc, -1, v122
	s_nop 1
	v_cndmask_b32_e32 v19, v205, v19, vcc
	v_cmp_lt_i32_e32 vcc, -1, v123
	s_nop 1
	v_cndmask_b32_e32 v18, v205, v18, vcc
	v_cmp_lt_i32_e32 vcc, -1, v107
	s_nop 1
	v_cndmask_b32_e32 v17, v205, v17, vcc
	v_cmp_lt_i32_e32 vcc, -1, v91
	s_nop 1
	v_cndmask_b32_e32 v16, v205, v16, vcc
	v_cmp_lt_i32_e32 vcc, 31, v134
	s_nop 1
	v_cndmask_b32_e32 v15, v205, v15, vcc
	v_cmp_lt_i32_e32 vcc, 31, v51
	s_nop 1
	v_cndmask_b32_e32 v14, v205, v14, vcc
	v_cmp_lt_i32_e32 vcc, 31, v132
	s_nop 1
	v_cndmask_b32_e32 v13, v205, v13, vcc
	v_cmp_lt_i32_e32 vcc, 31, v133
	s_nop 1
	v_cndmask_b32_e32 v12, v205, v12, vcc
	v_cmp_lt_i32_e32 vcc, 31, v130
	s_nop 1
	v_cndmask_b32_e32 v11, v205, v11, vcc
	v_cmp_lt_i32_e32 vcc, 31, v131
	s_nop 1
	v_cndmask_b32_e32 v10, v205, v10, vcc
	v_cmp_lt_i32_e32 vcc, 31, v128
	s_nop 1
	v_cndmask_b32_e32 v9, v205, v9, vcc
	v_cmp_lt_i32_e32 vcc, 31, v129
	s_nop 1
	v_cndmask_b32_e32 v8, v205, v8, vcc
	v_cmp_lt_i32_e32 vcc, 31, v126
	s_nop 1
	v_cndmask_b32_e32 v7, v205, v7, vcc
	v_cmp_lt_i32_e32 vcc, 31, v127
	s_nop 1
	v_cndmask_b32_e32 v6, v205, v6, vcc
	v_cmp_lt_i32_e32 vcc, 31, v124
	s_nop 1
	v_cndmask_b32_e32 v5, v205, v5, vcc
	v_cmp_lt_i32_e32 vcc, 31, v125
	s_nop 1
	v_cndmask_b32_e32 v4, v205, v4, vcc
	v_cmp_lt_i32_e32 vcc, 31, v122
	s_nop 1
	v_cndmask_b32_e32 v3, v205, v3, vcc
	v_cmp_lt_i32_e32 vcc, 31, v123
	s_nop 1
	v_cndmask_b32_e32 v2, v205, v2, vcc
	v_cmp_lt_i32_e32 vcc, 31, v107
	s_nop 1
	v_cndmask_b32_e32 v1, v205, v1, vcc
	v_cmp_lt_i32_e32 vcc, 31, v91
	s_nop 1
	v_cndmask_b32_e32 v0, v205, v0, vcc

; #define ALAS __attribute__((address_space(3)))
; __device__ __forceinline__ void moba_unit(int b, int h, int j, const bf16_t* Q, const bf16_t* K, const bf16_t* VT, bf16_t* O, const float* biasd, const float* kmean, ALAS unsigned char* lds) {
;     ...
;     for (int t = 0; t < NT; ++t) {
;         ALAS unsigned char* buf = lds + (t & 1) * 18432;
;         *(ALAS u32x4*)(buf + kl) = kr; *(ALAS u32x4*)(buf + vl) = vr;
;         __syncthreads();
;         if (t + 1 < NT) { const int t1 = t + 1; const int kb1 = (t1 < 4) ? (256 * j + 64 * t1) : (64 * (t1 - 4));
;             kr = *(const u32x4*)(kg + (size_t)kb1 * 1024); vr = *(const u32x4*)(vg + kb1); }
.Lmb_533b:
	s_add_i32 s8, s16, 4
	s_bitcmp1_b32 s8, 0
	s_cselect_b32 s0, 0x4800, 0
	s_add_i32 s17, s0, 0
	s_add_i32 s0, s16, 5
	v_add3_u32 v32, s17, v104, v92
	s_cmp_lt_i32 s0, s14
	s_cbranch_scc1 .Lmb_wnextb
	s_waitcnt vmcnt(0)
	s_branch .Lmb_wgob
.Lmb_wnextb:
	s_waitcnt vmcnt(2)
.Lmb_wgob:
	ds_write_b128 v32, v[160:163]
	ds_write_b128 v32, v[164:167] offset:9216
	s_add_i32 s18, s96, s15
	s_add_i32 s0, s16, 6
	s_cmp_lt_i32 s0, s14
	s_waitcnt lgkmcnt(0)
	s_barrier
	v_add3_u32 v216, s17, v105, v144
	ds_read_b128 v[108:111], v216 offset:0
	ds_read_b128 v[112:115], v216 offset:4608
	ds_read_b128 v[116:119], v216 offset:32
	ds_read_b128 v[120:123], v216 offset:4640
	ds_read_b128 v[124:127], v216 offset:64
	ds_read_b128 v[128:131], v216 offset:4672
	ds_read_b128 v[132:135], v216 offset:96
	ds_read_b128 v[136:139], v216 offset:4704
	s_cbranch_scc0 .Lmb_537b
	s_add_i32 s0, s18, 0x180
	s_add_i32 s1, s15, 0x80
	s_cmp_lt_u32 s8, 2
	s_cselect_b32 s0, s0, s1
	s_ashr_i32 s1, s0, 31
	s_lshl_b64 s[6:7], s[0:1], 11
	v_lshl_add_u64 v[32:33], v[94:95], 0, s[6:7]
	v_lshl_add_u64 v[34:35], s[0:1], 1, v[96:97]
	global_load_dwordx4 v[160:163], v[32:33], off
	global_load_dwordx4 v[164:167], v[34:35], off

; #define ALAS __attribute__((address_space(3)))
; __device__ __forceinline__ float ex2(float x) { return __builtin_amdgcn_exp2f(x); }
; template <int NDB> __device__ __forceinline__ void wait_v(bf16x8 (&v)[2 * NDB]) { if constexpr (NDB == 4) lds_wait8(v); else lds_wait4(v); }
; template <int NDB>
; __device__ __forceinline__ void softmax_pv(f32x16& s0, f32x16& s1, float& mref, float& lsum, f32x16 (&o)[NDB], const ALAS unsigned char* Vb, int r32, int hi) {
;     const unsigned vp = (unsigned)(uintptr_t)(Vb + r32 * ROWB + hi * 16);
;     bf16x8 va[2 * NDB], vb[2 * NDB];
;     issue_v<NDB, 0>(va, vp);
;     float ps = 0.f;
; #pragma unroll
;     for (int r = 0; r < 16; ++r) { s0[r] = ex2(s0[r]); ps += s0[r]; }
;     bf16x8 pf0, pf1, pf2, pf3;
;     pack16(s0, pf0, pf1);
;     wait_v<NDB>(va);
;     issue_v<NDB, 1>(vb, vp);
;     __builtin_amdgcn_sched_barrier(0);
; #pragma unroll
;     for (int d = 0; d < NDB; ++d) o[d] = __builtin_amdgcn_mfma_f32_32x32x16_bf16(va[d], pf0, o[d], 0, 0, 0);
; #pragma unroll
;     for (int d = 0; d < NDB; ++d) o[d] = __builtin_amdgcn_mfma_f32_32x32x16_bf16(va[NDB + d], pf1, o[d], 0, 0, 0);
; #pragma unroll
;     for (int r = 0; r < 16; ++r) { s1[r] = ex2(s1[r]); ps += s1[r]; }
;     pack16(s1, pf2, pf3);
; #pragma unroll
;     for (int i = 0; i < 2 * NDB; ++i) { __builtin_amdgcn_sched_group_barrier(0x008, 1, 0); __builtin_amdgcn_sched_group_barrier(0x002, (NDB == 4 ? 5 : 10), 0); }
;     __builtin_amdgcn_sched_barrier(0);
;     wait_v<NDB>(vb);
;     __builtin_amdgcn_sched_barrier(0);
; #pragma unroll
;     for (int d = 0; d < NDB; ++d) o[d] = __builtin_amdgcn_mfma_f32_32x32x16_bf16(vb[d], pf2, o[d], 0, 0, 0);
; #pragma unroll
;     for (int d = 0; d < NDB; ++d) o[d] = __builtin_amdgcn_mfma_f32_32x32x16_bf16(vb[NDB + d], pf3, o[d], 0, 0, 0);
;     lsum += ps;
;     if (__any(ps > 1048576.0f)) {
;         const float pt = ps + __shfl_xor(ps, 32); const float dl = pt > 1048576.0f ? floorf(__log2f(pt)) : 0.f, al = ex2(-dl); mref += dl; lsum *= al;
; #pragma unroll
;         for (int d = 0; d < NDB; ++d)
; #pragma unroll
;             for (int r = 0; r < 16; ++r) o[d][r] *= al;
;     }
; }
; __device__ __forceinline__ void moba_unit(int b, int h, int j, const bf16_t* Q, const bf16_t* K, const bf16_t* VT, bf16_t* O, const float* biasd, const float* kmean, ALAS unsigned char* lds) {
;     ...
;     for (int t = 0; t < NT; ++t) {
.Lmb_544b:
	v_add_u32_e32 v102, s17, v106
	v_add3_u32 v102, v102, v144, s95
	ds_read_b128 v[108:111], v102 offset:0
	ds_read_b128 v[112:115], v102 offset:4608
	ds_read_b128 v[116:119], v102 offset:32
	ds_read_b128 v[120:123], v102 offset:4640
	s_nop 7
	v_exp_f32_e32 v139, v56
	v_exp_f32_e32 v140, v57
	v_exp_f32_e32 v141, v58
	v_exp_f32_e32 v142, v59
	ds_read_b128 v[56:59], v102 offset:64
	v_exp_f32_e32 v143, v60
	v_exp_f32_e32 v156, v61
	v_exp_f32_e32 v157, v62
	v_exp_f32_e32 v158, v63
	ds_read_b128 v[60:63], v102 offset:4672
	v_exp_f32_e32 v103, v48
	v_exp_f32_e32 v132, v49
	v_exp_f32_e32 v133, v50
	v_exp_f32_e32 v134, v51
	v_exp_f32_e32 v135, v52
	v_exp_f32_e32 v136, v53
	v_exp_f32_e32 v137, v54
	v_exp_f32_e32 v138, v55
	ds_read_b128 v[124:127], v102 offset:96
	ds_read_b128 v[128:131], v102 offset:4704
	v_cvt_pk_bf16_f32 v48, v103, v132
	v_cvt_pk_bf16_f32 v49, v133, v134
	v_cvt_pk_bf16_f32 v50, v135, v136
	v_cvt_pk_bf16_f32 v51, v137, v138
	v_cvt_pk_bf16_f32 v52, v139, v140
	v_cvt_pk_bf16_f32 v53, v141, v142
	v_cvt_pk_bf16_f32 v54, v143, v156
	v_cvt_pk_bf16_f32 v55, v157, v158
	s_waitcnt lgkmcnt(4)
	v_mfma_f32_32x32x16_bf16 v[16:31], v[108:111], v[48:51], v[16:31]
	v_add_f32_e32 v102, 0, v103
	v_add_f32_e32 v102, v132, v102
	v_add_f32_e32 v102, v133, v102
	v_add_f32_e32 v102, v134, v102
	v_add_f32_e32 v102, v135, v102
	v_add_f32_e32 v102, v136, v102
	v_add_f32_e32 v102, v137, v102
	v_add_f32_e32 v102, v138, v102
	v_add_f32_e32 v102, v139, v102
	v_add_f32_e32 v102, v140, v102
	v_mfma_f32_32x32x16_bf16 v[0:15], v[112:115], v[48:51], v[0:15]
	v_add_f32_e32 v48, v141, v102
	v_add_f32_e32 v48, v142, v48
	v_add_f32_e32 v48, v143, v48
	v_exp_f32_e32 v49, v32
	v_add_f32_e32 v48, v156, v48
	v_exp_f32_e32 v50, v33
	v_add_f32_e32 v48, v157, v48
	v_exp_f32_e32 v51, v34
	v_add_f32_e32 v48, v158, v48
	v_exp_f32_e32 v102, v35
	v_exp_f32_e32 v103, v36
	v_add_f32_e32 v48, v49, v48
	v_exp_f32_e32 v108, v37
	v_add_f32_e32 v48, v50, v48
	v_exp_f32_e32 v109, v38
	v_exp_f32_e32 v110, v39
	v_exp_f32_e32 v40, v40
	v_exp_f32_e32 v41, v41
	v_exp_f32_e32 v42, v42
	v_exp_f32_e32 v43, v43
	v_exp_f32_e32 v44, v44
	v_exp_f32_e32 v45, v45
	v_exp_f32_e32 v46, v46
	v_exp_f32_e32 v47, v47
	v_add_f32_e32 v48, v51, v48
	v_add_f32_e32 v48, v102, v48
	v_add_f32_e32 v48, v103, v48
	v_add_f32_e32 v48, v108, v48
	v_cvt_pk_bf16_f32 v32, v49, v50
	v_cvt_pk_bf16_f32 v33, v51, v102
	v_cvt_pk_bf16_f32 v34, v103, v108
	v_cvt_pk_bf16_f32 v35, v109, v110
	v_mfma_f32_32x32x16_bf16 v[16:31], v[116:119], v[52:55], v[16:31]
	v_cvt_pk_bf16_f32 v36, v40, v41
	v_cvt_pk_bf16_f32 v37, v42, v43
	v_cvt_pk_bf16_f32 v38, v44, v45
	v_cvt_pk_bf16_f32 v39, v46, v47
	v_add_f32_e32 v48, v109, v48
	v_add_f32_e32 v48, v110, v48
	v_add_f32_e32 v40, v40, v48
	v_mfma_f32_32x32x16_bf16 v[0:15], v[120:123], v[52:55], v[0:15]
	v_add_f32_e32 v40, v41, v40
	v_add_f32_e32 v40, v42, v40
	v_add_f32_e32 v40, v43, v40
	v_add_f32_e32 v40, v44, v40
	v_add_f32_e32 v40, v45, v40
	v_add_f32_e32 v40, v46, v40
	s_waitcnt lgkmcnt(0)
	s_nop 0
	v_mfma_f32_32x32x16_bf16 v[16:31], v[56:59], v[32:35], v[16:31]
	v_mfma_f32_32x32x16_bf16 v[0:15], v[60:63], v[32:35], v[0:15]
	v_add_f32_e32 v32, v47, v40
	v_add_f32_e32 v100, v100, v32
	v_cmp_lt_f32_e32 vcc, s34, v32
	v_mfma_f32_32x32x16_bf16 v[16:31], v[124:127], v[36:39], v[16:31]
	v_mfma_f32_32x32x16_bf16 v[0:15], v[128:131], v[36:39], v[0:15]
	s_cbranch_vccz .Lmb_532b
	ds_bpermute_b32 v33, v93, v32
	s_waitcnt lgkmcnt(0)
	v_add_f32_e32 v32, v32, v33
	v_log_f32_e32 v33, v32
	v_cmp_lt_f32_e32 vcc, s34, v32
	v_floor_f32_e32 v33, v33
	s_nop 0
	v_cndmask_b32_e32 v33, 0, v33, vcc
	v_exp_f32_e64 v32, -v33
	v_add_f32_e32 v101, v101, v33
	v_mul_f32_e32 v100, v100, v32
	v_pk_mul_f32 v[30:31], v[30:31], v[32:33] op_sel_hi:[1,0]
	v_pk_mul_f32 v[28:29], v[28:29], v[32:33] op_sel_hi:[1,0]
	v_pk_mul_f32 v[26:27], v[26:27], v[32:33] op_sel_hi:[1,0]
	v_pk_mul_f32 v[24:25], v[24:25], v[32:33] op_sel_hi:[1,0]
	v_pk_mul_f32 v[22:23], v[22:23], v[32:33] op_sel_hi:[1,0]
	v_pk_mul_f32 v[20:21], v[20:21], v[32:33] op_sel_hi:[1,0]
	v_pk_mul_f32 v[18:19], v[18:19], v[32:33] op_sel_hi:[1,0]
	v_pk_mul_f32 v[16:17], v[16:17], v[32:33] op_sel_hi:[1,0]
	v_pk_mul_f32 v[14:15], v[14:15], v[32:33] op_sel_hi:[1,0]
	v_pk_mul_f32 v[12:13], v[12:13], v[32:33] op_sel_hi:[1,0]
	v_pk_mul_f32 v[10:11], v[10:11], v[32:33] op_sel_hi:[1,0]
	v_pk_mul_f32 v[8:9], v[8:9], v[32:33] op_sel_hi:[1,0]
	v_pk_mul_f32 v[6:7], v[6:7], v[32:33] op_sel_hi:[1,0]
	v_pk_mul_f32 v[4:5], v[4:5], v[32:33] op_sel_hi:[1,0]
	v_pk_mul_f32 v[2:3], v[2:3], v[32:33] op_sel_hi:[1,0]
	v_pk_mul_f32 v[0:1], v[0:1], v[32:33] op_sel_hi:[1,0]
	s_branch .Lmb_532b
.Lmb_532b:
	s_add_i32 s15, s15, 64
	s_add_i32 s16, s16, 1
	s_cmp_lg_u32 s13, s16
	s_cbranch_scc0 .LBB0_517

; #define ALAS __attribute__((address_space(3)))
; __device__ __forceinline__ void moba_unit(int b, int h, int j, const bf16_t* Q, const bf16_t* K, const bf16_t* VT, bf16_t* O, const float* biasd, const float* kmean, ALAS unsigned char* lds) {
;     ...
;     for (int t = 0; t < NT; ++t) {
;         ALAS unsigned char* buf = lds + (t & 1) * 18432;
;         *(ALAS u32x4*)(buf + kl) = kr; *(ALAS u32x4*)(buf + vl) = vr;
;         __syncthreads();
;         if (t + 1 < NT) { const int t1 = t + 1; const int kb1 = (t1 < 4) ? (256 * j + 64 * t1) : (64 * (t1 - 4));
;             kr = *(const u32x4*)(kg + (size_t)kb1 * 1024); vr = *(const u32x4*)(vg + kb1); }
.Lmb_wgo:
	ds_write_b128 v32, v[80:83]
	ds_write_b128 v32, v[84:87] offset:9216
	s_add_i32 s18, s96, s15
	s_add_i32 s0, s16, 6
	s_cmp_lt_i32 s0, s14
	s_waitcnt lgkmcnt(0)
	s_barrier
	v_add3_u32 v216, s17, v105, v144
	ds_read_b128 v[108:111], v216 offset:0
	ds_read_b128 v[112:115], v216 offset:4608
	ds_read_b128 v[116:119], v216 offset:32
	ds_read_b128 v[120:123], v216 offset:4640
	ds_read_b128 v[124:127], v216 offset:64
	ds_read_b128 v[128:131], v216 offset:4672
	ds_read_b128 v[132:135], v216 offset:96
	ds_read_b128 v[136:139], v216 offset:4704
	s_cbranch_scc0 .LBB0_537
	s_add_i32 s0, s18, 0x180
	s_add_i32 s1, s15, 0x80
	s_cmp_lt_u32 s8, 2
	s_cselect_b32 s0, s0, s1
	s_ashr_i32 s1, s0, 31
	s_lshl_b64 s[6:7], s[0:1], 11
	v_lshl_add_u64 v[32:33], v[94:95], 0, s[6:7]
	v_lshl_add_u64 v[34:35], s[0:1], 1, v[96:97]
	global_load_dwordx4 v[80:83], v[32:33], off
	global_load_dwordx4 v[84:87], v[34:35], off
